# v27 + specialised lean GEMM epilogue for store modes 0 and 3 (in-place bf16 convert, scalar address stepping, sc1 stores)
# baseline (speedup 1.0000x reference)
;     __device__ __forceinline__ void operator()(const f32x4 (&acc)[2][2][4][2], const pg8::Unit& u, int wr, int wc, int fr, int fq) const {
;     ...
;                 for (int m = 0; m < 4; ++m) { const int row = row0 + ai * 128 + m * 16; bf16_t* rowp = O + (size_t)row * ldc + col0; const int pos = row & (SEQ - 1);
;                     const int dcol = wc * 32 + 8 * fq, sq4 = row & ~(SEQ - 1);
; #pragma unroll
;                     for (int bj = 0; bj < 2; ++bj) { f32x4 v0 = acc[ai][bj][m][0], v1 = acc[ai][bj][m][1];
;                         if (mode == 1) {
;                             const int col = col0 + bj * 128; const int d = col % 96;
;                             if (d >= 64) { const int f0 = (d - 64) >> 1;
;                                 const f32x4 c = *(const f32x4*)(cs + pos * 32 + f0), s = *(const f32x4*)(cs + pos * 32 + 16 + f0);
;                                 f32x4 a0, a1;
;                                 a0[0] = v0[0] * c[0] - v0[1] * s[0]; a0[1] = v0[0] * s[0] + v0[1] * c[0];
;                                 a0[2] = v0[2] * c[1] - v0[3] * s[1]; a0[3] = v0[2] * s[1] + v0[3] * c[1];
;                                 a1[0] = v1[0] * c[2] - v1[1] * s[2]; a1[1] = v1[0] * s[2] + v1[1] * c[2];
;                                 a1[2] = v1[2] * c[3] - v1[3] * s[3]; a1[3] = v1[2] * s[3] + v1[3] * c[3];
;                                 v0 = a0; v1 = a1; }
;                             v0 = v0 * scale; v1 = v1 * scale; }
.LBB0_312:
	s_lshl_b32 s31, s31, 8
	s_add_i32 s31, s31, s97
	s_lshl_b32 s65, s64, 8
	v_or_b32_e32 v164, s31, v159
	v_or_b32_e32 v136, s65, v158
	s_andn2_b64 vcc, exec, s[26:27]
	s_mov_b64 s[10:11], -1
	s_cbranch_vccnz .LBB0_506
	s_and_b64 vcc, exec, s[12:13]
	s_cbranch_vccz .Lepi_lean
	s_mov_b32 s10, 0x2aaaaaab
	v_mul_hi_i32 v128, v136, s10
	v_and_b32_e32 v142, 0xfcf, v164
	v_lshrrev_b32_e32 v144, 31, v128
	v_lshrrev_b32_e32 v145, 4, v128
	v_mov_b64_e32 v[134:135], v[122:123]
	v_mov_b64_e32 v[130:131], v[126:127]
	v_lshlrev_b32_e32 v143, 5, v142
	s_and_b64 vcc, exec, s[12:13]
	v_mov_b64_e32 v[132:133], v[120:121]
	v_mov_b64_e32 v[128:129], v[124:125]
	s_cbranch_vccz .LBB0_317
	v_add_u32_e32 v128, v145, v144
	v_mul_lo_u32 v128, v128, s66
	v_sub_u32_e32 v137, v136, v128
	v_cmp_lt_i32_e32 vcc, 63, v137
	v_mov_b32_e32 v128, v124
	v_mov_b32_e32 v129, v125
	v_mov_b32_e32 v130, v126
	v_mov_b32_e32 v131, v127
	v_mov_b32_e32 v132, v120
	v_mov_b32_e32 v133, v121
	v_mov_b32_e32 v134, v122
	v_mov_b32_e32 v135, v123
	s_and_saveexec_b64 s[10:11], vcc
	s_cbranch_execz .LBB0_316
	v_subrev_u32_e32 v128, 64, v137
	v_lshlrev_b32_e32 v178, 2, v143
	v_lshrrev_b32_e32 v128, 1, v128
	v_lshl_add_u64 v[130:131], s[72:73], 0, v[178:179]
	v_mov_b32_e32 v129, v179
	v_lshl_add_u64 v[128:129], v[128:129], 2, v[130:131]
	global_load_dwordx4 v[138:141], v[128:129], off
	global_load_dwordx4 v[166:169], v[128:129], off offset:64
	s_waitcnt vmcnt(0)
	v_pk_mul_f32 v[170:171], v[124:125], v[138:139]
	v_pk_mul_f32 v[146:147], v[124:125], v[166:167] op_sel:[1,0] op_sel_hi:[0,0]
	v_pk_fma_f32 v[128:129], v[124:125], v[138:139], v[146:147] op_sel_hi:[1,0,1]
	v_mov_b32_e32 v166, v139
	v_mul_f32_e32 v128, v127, v167
	v_pk_fma_f32 v[130:131], v[126:127], v[166:167], v[128:129] op_sel_hi:[1,1,0] neg_lo:[0,0,1] neg_hi:[0,0,1]
	v_mov_b32_e32 v138, v167
	v_mul_f32_e32 v128, v127, v139
	v_pk_fma_f32 v[138:139], v[126:127], v[138:139], v[128:129] op_sel_hi:[1,1,0]
	v_pk_mul_f32 v[166:167], v[120:121], v[168:169] op_sel:[1,0] op_sel_hi:[0,0]
	v_mov_b32_e32 v168, v141
	v_mul_f32_e32 v128, v123, v169
	v_pk_mul_f32 v[172:173], v[120:121], v[140:141]
	v_pk_fma_f32 v[132:133], v[120:121], v[140:141], v[166:167] op_sel_hi:[1,0,1]
	v_pk_fma_f32 v[134:135], v[122:123], v[168:169], v[128:129] op_sel_hi:[1,1,0] neg_lo:[0,0,1] neg_hi:[0,0,1]
	v_mov_b32_e32 v140, v169
	v_mul_f32_e32 v128, v123, v141
	v_pk_fma_f32 v[140:141], v[122:123], v[140:141], v[128:129] op_sel_hi:[1,1,0]
	v_sub_f32_e32 v128, v170, v146
	v_sub_f32_e32 v132, v172, v166
	v_mov_b32_e32 v131, v138
	v_mov_b32_e32 v135, v140

; __device__ __forceinline__ unsigned cvtpk(float lo, float hi) { f32x2_t v = {lo, hi}; bf16x2_t b = __builtin_convertvector(v, bf16x2_t); return __builtin_bit_cast(unsigned, b); }
;     __device__ __forceinline__ void operator()(const f32x4 (&acc)[2][2][4][2], const pg8::Unit& u, int wr, int wc, int fr, int fq) const {
;     ...
;                 for (int m = 0; m < 4; ++m) { const int row = row0 + ai * 128 + m * 16; bf16_t* rowp = O + (size_t)row * ldc + col0; const int pos = row & (SEQ - 1);
;                     const int dcol = wc * 32 + 8 * fq, sq4 = row & ~(SEQ - 1);
; #pragma unroll
;                     for (int bj = 0; bj < 2; ++bj) { f32x4 v0 = acc[ai][bj][m][0], v1 = acc[ai][bj][m][1];
;                         if (mode == 1) {
;                             const int col = col0 + bj * 128; const int d = col % 96;
;                             if (d >= 64) { const int f0 = (d - 64) >> 1;
;                                 const f32x4 c = *(const f32x4*)(cs + pos * 32 + f0), s = *(const f32x4*)(cs + pos * 32 + 16 + f0);
;                                 f32x4 a0, a1;
;                                 a0[0] = v0[0] * c[0] - v0[1] * s[0]; a0[1] = v0[0] * s[0] + v0[1] * c[0];
;                                 a0[2] = v0[2] * c[1] - v0[3] * s[1]; a0[3] = v0[2] * s[1] + v0[3] * c[1];
;                                 a1[0] = v1[0] * c[2] - v1[1] * s[2]; a1[1] = v1[0] * s[2] + v1[1] * c[2];
;                                 a1[2] = v1[2] * c[3] - v1[3] * s[3]; a1[3] = v1[2] * s[3] + v1[3] * c[3];
;                                 v0 = a0; v1 = a1; }
;                             v0 = v0 * scale; v1 = v1 * scale; }
;                         u32x4 w; w.x = cvtpk(v0[0], v0[1]); w.y = cvtpk(v0[2], v0[3]); w.z = cvtpk(v1[0], v1[1]); w.w = cvtpk(v1[2], v1[3]);
;                         if (mode == 3) { const int cb = u.pn * 2 + bj;
;                             bf16_t* dst;
;                             if (cb < 72) { const int dsh = 2 * (cb / 24); const int tp = sq4 + ((pos & ((1 << dsh) - 1)) << (12 - dsh)) + (pos >> dsh); dst = O + ((size_t)cb * ldc + tp) * 128 + dcol; }
;                             else dst = O + (size_t)9216 * ldc + (size_t)row * 1024 + (cb - 72) * 128 + dcol;
;                             *(u32x4*)dst = w; }
;                         else *(u32x4*)(rowp + bj * 128) = w; }
.Lepi_lean:
	v_lshlrev_b32_e32 v144, 1, v158
	s_and_b64 vcc, exec, s[28:29]
	s_cbranch_vccnz .Lepi_m0
	s_cmp_gt_i32 s64, 35
	s_cbranch_scc1 .Lepi_gate
	s_and_b32 s79, s31, 0xfff
	s_andn2_b32 s76, s31, 0xfff
	s_lshl_b32 s74, s64, 1
	s_mul_i32 s74, s74, s40
	s_cmp_lt_i32 s64, 12
	s_cbranch_scc1 .Lepi_g0
	s_cmp_lt_i32 s64, 24
	s_cbranch_scc1 .Lepi_g1
	s_lshr_b32 s79, s79, 4
	v_lshl_add_u32 v145, v159, 16, v144
	s_movk_i32 s75, 0x100
	s_movk_i32 s10, 0x500
	s_branch .Lepi_gcommon
.Lepi_g1:
	s_lshr_b32 s79, s79, 2
	v_and_b32_e32 v146, 3, v159
	v_lshrrev_b32_e32 v147, 2, v159
	v_lshl_add_u32 v145, v146, 18, v144
	v_lshl_add_u32 v145, v147, 8, v145
	s_movk_i32 s75, 0x400
	s_movk_i32 s10, 0x1400
	s_branch .Lepi_gcommon
.Lepi_g0:
	v_lshl_add_u32 v145, v159, 8, v144
	s_movk_i32 s75, 0x1000
	s_movk_i32 s10, 0x5000
.Lepi_gcommon:
	s_add_i32 s76, s76, s79
	s_add_i32 s74, s74, s76
	s_lshl_b32 s74, s74, 8
	s_mov_b32 s79, s10
	s_add_u32 s10, s20, s74
	s_addc_u32 s11, s21, 0
	s_lshl_b32 s74, s40, 8
	s_add_u32 s86, s10, s74
	s_addc_u32 s87, s11, 0
	s_branch .Lepi_store
.Lepi_gate:
	s_lshl_b32 s74, s31, 11
	s_lshl_b32 s76, s64, 9
	s_add_i32 s74, s74, s76
	s_sub_u32 s74, s74, 0x4800
	v_lshl_add_u32 v145, v159, 11, v144
	s_add_u32 s10, s36, s74
	s_addc_u32 s11, s37, 0
	s_add_u32 s86, s10, 0x100
	s_addc_u32 s87, s11, 0
	s_mov_b32 s75, 0x8000
	s_mov_b32 s79, 0x28000
	s_branch .Lepi_store
.Lepi_m0:
	s_mul_i32 s74, s31, s40
	s_lshl_b32 s76, s64, 8
	s_add_i32 s74, s74, s76
	s_lshl_b32 s74, s74, 1
	s_add_u32 s10, s22, s74
	s_addc_u32 s11, s23, 0
	s_add_u32 s86, s10, 0x100
	s_addc_u32 s87, s11, 0
	s_lshl_b32 s75, s40, 5
	s_lshl_b32 s79, s40, 8
	s_mul_i32 s74, s75, 3
	s_sub_i32 s79, s79, s74
	s_lshl_b32 s74, s40, 1
	v_mul_lo_u32 v145, v159, s74
	v_add_u32_e32 v145, v145, v144
.Lepi_store:
	v_cvt_pk_bf16_f32 v124, v124, v125
	v_cvt_pk_bf16_f32 v125, v126, v127
	v_cvt_pk_bf16_f32 v126, v120, v121
	v_cvt_pk_bf16_f32 v127, v122, v123
	global_store_dwordx4 v145, v[124:127], s[10:11] sc1
	v_cvt_pk_bf16_f32 v108, v108, v109
	v_cvt_pk_bf16_f32 v109, v110, v111
	v_cvt_pk_bf16_f32 v110, v104, v105
	v_cvt_pk_bf16_f32 v111, v106, v107
	global_store_dwordx4 v145, v[108:111], s[86:87] sc1
	s_add_u32 s10, s10, s75
	s_addc_u32 s11, s11, 0
	s_add_u32 s86, s86, s75
	s_addc_u32 s87, s87, 0
	v_cvt_pk_bf16_f32 v116, v116, v117
	v_cvt_pk_bf16_f32 v117, v118, v119
	v_cvt_pk_bf16_f32 v118, v112, v113
	v_cvt_pk_bf16_f32 v119, v114, v115
	global_store_dwordx4 v145, v[116:119], s[10:11] sc1
	v_cvt_pk_bf16_f32 v100, v100, v101
	v_cvt_pk_bf16_f32 v101, v102, v103
	v_cvt_pk_bf16_f32 v102, v96, v97
	v_cvt_pk_bf16_f32 v103, v98, v99
	global_store_dwordx4 v145, v[100:103], s[86:87] sc1
	s_add_u32 s10, s10, s75
	s_addc_u32 s11, s11, 0
	s_add_u32 s86, s86, s75
	s_addc_u32 s87, s87, 0
	v_cvt_pk_bf16_f32 v92, v92, v93
	v_cvt_pk_bf16_f32 v93, v94, v95
	v_cvt_pk_bf16_f32 v94, v88, v89
	v_cvt_pk_bf16_f32 v95, v90, v91
	global_store_dwordx4 v145, v[92:95], s[10:11] sc1
	v_cvt_pk_bf16_f32 v84, v84, v85
	v_cvt_pk_bf16_f32 v85, v86, v87
	v_cvt_pk_bf16_f32 v86, v80, v81
	v_cvt_pk_bf16_f32 v87, v82, v83
	global_store_dwordx4 v145, v[84:87], s[86:87] sc1
	s_add_u32 s10, s10, s75
	s_addc_u32 s11, s11, 0
	s_add_u32 s86, s86, s75
	s_addc_u32 s87, s87, 0
	v_cvt_pk_bf16_f32 v76, v76, v77
	v_cvt_pk_bf16_f32 v77, v78, v79
	v_cvt_pk_bf16_f32 v78, v72, v73
	v_cvt_pk_bf16_f32 v79, v74, v75
	global_store_dwordx4 v145, v[76:79], s[10:11] sc1
	v_cvt_pk_bf16_f32 v68, v68, v69
	v_cvt_pk_bf16_f32 v69, v70, v71
	v_cvt_pk_bf16_f32 v70, v64, v65
	v_cvt_pk_bf16_f32 v71, v66, v67
	global_store_dwordx4 v145, v[68:71], s[86:87] sc1
	s_add_u32 s10, s10, s79
	s_addc_u32 s11, s11, 0
	s_add_u32 s86, s86, s79
	s_addc_u32 s87, s87, 0
	v_cvt_pk_bf16_f32 v60, v60, v61
	v_cvt_pk_bf16_f32 v61, v62, v63
	v_cvt_pk_bf16_f32 v62, v56, v57
	v_cvt_pk_bf16_f32 v63, v58, v59
	global_store_dwordx4 v145, v[60:63], s[10:11] sc1
	v_cvt_pk_bf16_f32 v52, v52, v53
	v_cvt_pk_bf16_f32 v53, v54, v55
	v_cvt_pk_bf16_f32 v54, v48, v49
	v_cvt_pk_bf16_f32 v55, v50, v51
	global_store_dwordx4 v145, v[52:55], s[86:87] sc1
	s_add_u32 s10, s10, s75
	s_addc_u32 s11, s11, 0
	s_add_u32 s86, s86, s75
	s_addc_u32 s87, s87, 0
	v_cvt_pk_bf16_f32 v44, v44, v45
	v_cvt_pk_bf16_f32 v45, v46, v47
	v_cvt_pk_bf16_f32 v46, v40, v41
	v_cvt_pk_bf16_f32 v47, v42, v43
	global_store_dwordx4 v145, v[44:47], s[10:11] sc1
	v_cvt_pk_bf16_f32 v36, v36, v37
	v_cvt_pk_bf16_f32 v37, v38, v39
	v_cvt_pk_bf16_f32 v38, v32, v33
	v_cvt_pk_bf16_f32 v39, v34, v35
	global_store_dwordx4 v145, v[36:39], s[86:87] sc1
	s_add_u32 s10, s10, s75
	s_addc_u32 s11, s11, 0
	s_add_u32 s86, s86, s75
	s_addc_u32 s87, s87, 0
	v_cvt_pk_bf16_f32 v28, v28, v29
	v_cvt_pk_bf16_f32 v29, v30, v31
	v_cvt_pk_bf16_f32 v30, v24, v25
	v_cvt_pk_bf16_f32 v31, v26, v27
	global_store_dwordx4 v145, v[28:31], s[10:11] sc1
	v_cvt_pk_bf16_f32 v20, v20, v21
	v_cvt_pk_bf16_f32 v21, v22, v23
	v_cvt_pk_bf16_f32 v22, v16, v17
	v_cvt_pk_bf16_f32 v23, v18, v19
	global_store_dwordx4 v145, v[20:23], s[86:87] sc1
	s_add_u32 s10, s10, s75
	s_addc_u32 s11, s11, 0
	s_add_u32 s86, s86, s75
	s_addc_u32 s87, s87, 0
	v_cvt_pk_bf16_f32 v12, v12, v13
	v_cvt_pk_bf16_f32 v13, v14, v15
	v_cvt_pk_bf16_f32 v14, v8, v9
	v_cvt_pk_bf16_f32 v15, v10, v11
	global_store_dwordx4 v145, v[12:15], s[10:11] sc1
	v_cvt_pk_bf16_f32 v4, v4, v5
	v_cvt_pk_bf16_f32 v5, v6, v7
	v_cvt_pk_bf16_f32 v6, v0, v1
	v_cvt_pk_bf16_f32 v7, v2, v3
	global_store_dwordx4 v145, v[4:7], s[86:87] sc1
	s_branch .LBB0_510
